# GLA item phases: the static priority raise on waves 4-7 instead of 0-3 (attention prompt units unchanged)
# baseline (speedup 1.0000x reference)
; #define REP(k) _Pragma("unroll 1") for (int rep_ = 0; rep_ < ((((DUP_MASK) >> (k)) & 1) ? 2 : 1); ++rep_)
; __global__ void __launch_bounds__(512, 2) fwd(Args a) {
;     ...
;     if (IN(2)) REP(2) {
;         if (G == 256 && !MK_MULTI) {
;             GlaPre pf; gla_prefetch(pf, a, vcu >> 2, vcu & 3);
;             const int it4 = 1024 + (vcu & 127);
; #pragma unroll 1
;             for (int it = vcu; it < 1024; it += G) gla_item<0>(a, lds, it >> 2, it & 3, pf, (it + G < 1024) ? it + G : it4);
.LBB0_371:
	s_cmp_lt_i32 s30, 3
	s_cselect_b64 s[10:11], -1, 0
	s_and_b64 s[0:1], s[10:11], s[0:1]
	s_andn2_b64 vcc, exec, s[0:1]
	v_lshrrev_b32_e32 v168, 3, v0
	v_lshlrev_b32_e32 v169, 4, v0
	s_cbranch_vccnz .LBB0_488
	v_readfirstlane_b32 s98, v0
	s_nop 3
	s_lshr_b32 s98, s98, 6
	s_cmp_ge_u32 s98, 4
	s_cbranch_scc0 .Lprio_done_p2
	s_setprio 1

; #define REP(k) _Pragma("unroll 1") for (int rep_ = 0; rep_ < ((((DUP_MASK) >> (k)) & 1) ? 2 : 1); ++rep_)
; __global__ void __launch_bounds__(512, 2) fwd(Args a) {
;     ...
;     if (IN(4)) REP(4) {
;         { const int nit = (G == 256 && !MK_MULTI) ? 1024 : 1152;
;         GlaPre pf; if (vcu < nit) gla_prefetch(pf, a, vcu >> 2, vcu & 3);
; #pragma unroll 1
;         for (int it = vcu; it < nit; it += G) gla_item<1>(a, lds, it >> 2, it & 3, pf, (it + G < nit) ? it + G : -1); }
.LBB0_696:
	s_cmp_lt_i32 s30, 5
	s_cselect_b64 s[4:5], -1, 0
	s_and_b64 s[0:1], s[4:5], s[0:1]
	s_andn2_b64 vcc, exec, s[0:1]
	s_cbranch_vccnz .LBB0_721
	v_readfirstlane_b32 s98, v0
	s_nop 3
	s_lshr_b32 s98, s98, 6
	s_cmp_ge_u32 s98, 4
	s_cbranch_scc0 .Lprio_done_p4
	s_setprio 1
